# norm phases: row-3 residual loads prefetched into row-1 registers after they are consumed; counted waits
# speedup vs baseline: 1.0146x; 1.0023x over previous
.LBB0_361:
	s_add_i32 s2, s60, 1
	s_and_b64 vcc, exec, s[40:41]
	s_ashr_i32 s3, s2, 31
	s_cbranch_vccnz .LBB0_396
	s_lshl_b64 s[8:9], s[2:3], 12
	v_lshl_add_u64 v[32:33], v[84:85], 0, s[8:9]
	global_load_dwordx4 v[20:23], v[32:33], off
	global_load_dwordx4 v[24:27], v[32:33], off offset:16
	global_load_dwordx4 v[28:31], v[32:33], off offset:2048
	s_nop 0
	global_load_dwordx4 v[32:35], v[32:33], off offset:2064
	s_lshl_b64 s[52:53], s[2:3], 11
	s_waitcnt vmcnt(0)
	s_cbranch_execnz .LBB0_364
.LBB0_363:
	s_lshl_b64 s[52:53], s[2:3], 11
	s_waitcnt vmcnt(0)
	v_mov_b32_e32 v24, v228
	v_mov_b32_e32 v25, v229
	v_mov_b32_e32 v26, v230
	v_mov_b32_e32 v27, v231
	v_mov_b32_e32 v32, v232
	v_mov_b32_e32 v33, v233
	v_mov_b32_e32 v34, v234
	v_mov_b32_e32 v35, v235
	s_mov_b64 s[8:9], 0x1000
	v_lshl_add_u64 v[244:245], v[244:245], 0, s[8:9]
	global_load_dwordx4 v[228:231], v[244:245], off
	global_load_dwordx4 v[232:235], v[244:245], off offset:1024
	v_lshlrev_b32_e32 v20, 16, v24
	v_and_b32_e32 v21, 0xffff0000, v24
	v_lshlrev_b32_e32 v22, 16, v25
	v_and_b32_e32 v23, 0xffff0000, v25
	v_lshlrev_b32_e32 v24, 16, v26
	v_and_b32_e32 v25, 0xffff0000, v26
	v_lshlrev_b32_e32 v26, 16, v27
	v_and_b32_e32 v27, 0xffff0000, v27
	s_waitcnt vmcnt(2)
	v_lshlrev_b32_e32 v28, 16, v32
	v_and_b32_e32 v29, 0xffff0000, v32
	v_lshlrev_b32_e32 v30, 16, v33
	v_and_b32_e32 v31, 0xffff0000, v33
	v_lshlrev_b32_e32 v32, 16, v34
	v_and_b32_e32 v33, 0xffff0000, v34
	v_lshlrev_b32_e32 v34, 16, v35
	v_and_b32_e32 v35, 0xffff0000, v35
.LBB0_364:
	s_and_b64 vcc, exec, s[42:43]
	s_waitcnt vmcnt(2)
	v_mov_b32_e32 v36, v204
	v_mov_b32_e32 v37, v205
	v_mov_b32_e32 v38, v206
	v_mov_b32_e32 v39, v207
	v_mov_b32_e32 v40, v208
	v_mov_b32_e32 v41, v209
	v_mov_b32_e32 v42, v210
	v_mov_b32_e32 v43, v211
	v_lshlrev_b32_e32 v130, 16, v36
	v_and_b32_e32 v131, 0xffff0000, v36
	v_lshlrev_b32_e32 v140, 16, v37
	v_and_b32_e32 v141, 0xffff0000, v37
	v_lshlrev_b32_e32 v118, 16, v38
	v_and_b32_e32 v119, 0xffff0000, v38
	v_lshlrev_b32_e32 v120, 16, v39
	v_and_b32_e32 v121, 0xffff0000, v39
	s_waitcnt vmcnt(2)
	v_lshlrev_b32_e32 v122, 16, v40
	v_and_b32_e32 v123, 0xffff0000, v40
	v_lshlrev_b32_e32 v124, 16, v41
	v_and_b32_e32 v125, 0xffff0000, v41
	v_lshlrev_b32_e32 v126, 16, v42
	v_and_b32_e32 v127, 0xffff0000, v42
	v_lshlrev_b32_e32 v128, 16, v43
	v_and_b32_e32 v129, 0xffff0000, v43
	s_cbranch_vccnz .LBB0_366
	v_lshl_add_u64 v[40:41], v[88:89], 0, s[52:53]
	global_load_dwordx4 v[36:39], v[40:41], off
	s_waitcnt vmcnt(0)
	v_lshlrev_b32_e32 v42, 16, v36
	v_and_b32_e32 v43, 0xffff0000, v36
	v_lshlrev_b32_e32 v44, 16, v37
	v_and_b32_e32 v45, 0xffff0000, v37
	v_mul_f32_e32 v36, 0xbfb8aa3b, v42
	v_mul_f32_e32 v37, 0xbfb8aa3b, v43
	v_exp_f32_e32 v36, v36
	v_exp_f32_e32 v37, v37
	v_lshlrev_b32_e32 v46, 16, v38
	v_and_b32_e32 v38, 0xffff0000, v38
	v_add_f32_e32 v36, 1.0, v36
	v_add_f32_e32 v37, 1.0, v37
	v_rcp_f32_e32 v36, v36
	v_rcp_f32_e32 v37, v37
	v_lshlrev_b32_e32 v47, 16, v39
	v_and_b32_e32 v39, 0xffff0000, v39
	v_pk_mul_f32 v[130:131], v[36:37], v[130:131]
	v_mul_f32_e32 v36, 0xbfb8aa3b, v44
	v_mul_f32_e32 v37, 0xbfb8aa3b, v45
	v_exp_f32_e32 v36, v36
	v_exp_f32_e32 v37, v37
	v_add_f32_e32 v36, 1.0, v36
	v_add_f32_e32 v37, 1.0, v37
	v_rcp_f32_e32 v36, v36
	v_rcp_f32_e32 v37, v37
	s_nop 0
	v_pk_mul_f32 v[140:141], v[36:37], v[140:141]
	v_mul_f32_e32 v36, 0xbfb8aa3b, v46
	v_mul_f32_e32 v37, 0xbfb8aa3b, v38
	v_exp_f32_e32 v36, v36
	v_exp_f32_e32 v37, v37
	v_add_f32_e32 v36, 1.0, v36
	v_add_f32_e32 v37, 1.0, v37
	v_rcp_f32_e32 v36, v36
	v_rcp_f32_e32 v37, v37
	s_nop 0
	v_pk_mul_f32 v[118:119], v[36:37], v[118:119]
	v_mul_f32_e32 v36, 0xbfb8aa3b, v47
	v_mul_f32_e32 v37, 0xbfb8aa3b, v39
	v_exp_f32_e32 v36, v36
	v_exp_f32_e32 v37, v37
	v_add_f32_e32 v36, 1.0, v36
	v_add_f32_e32 v37, 1.0, v37
	v_rcp_f32_e32 v36, v36
	v_rcp_f32_e32 v37, v37
	s_nop 0
	v_pk_mul_f32 v[120:121], v[36:37], v[120:121]
	global_load_dwordx4 v[36:39], v[40:41], off offset:1024
	s_waitcnt vmcnt(0)
	v_lshlrev_b32_e32 v40, 16, v36
	v_and_b32_e32 v41, 0xffff0000, v36
	v_lshlrev_b32_e32 v42, 16, v37
	v_and_b32_e32 v43, 0xffff0000, v37
	v_mul_f32_e32 v36, 0xbfb8aa3b, v40
	v_mul_f32_e32 v37, 0xbfb8aa3b, v41
	v_exp_f32_e32 v36, v36
	v_exp_f32_e32 v37, v37
	v_lshlrev_b32_e32 v44, 16, v38
	v_and_b32_e32 v38, 0xffff0000, v38
	v_add_f32_e32 v36, 1.0, v36
	v_add_f32_e32 v37, 1.0, v37
	v_rcp_f32_e32 v36, v36
	v_rcp_f32_e32 v37, v37
	v_lshlrev_b32_e32 v45, 16, v39
	v_and_b32_e32 v39, 0xffff0000, v39
	v_pk_mul_f32 v[122:123], v[36:37], v[122:123]
	v_mul_f32_e32 v36, 0xbfb8aa3b, v42
	v_mul_f32_e32 v37, 0xbfb8aa3b, v43
	v_exp_f32_e32 v36, v36
	v_exp_f32_e32 v37, v37
	v_add_f32_e32 v36, 1.0, v36
	v_add_f32_e32 v37, 1.0, v37
	v_rcp_f32_e32 v36, v36
	v_rcp_f32_e32 v37, v37
	s_nop 0
	v_pk_mul_f32 v[124:125], v[36:37], v[124:125]
	v_mul_f32_e32 v36, 0xbfb8aa3b, v44
	v_mul_f32_e32 v37, 0xbfb8aa3b, v38
	v_exp_f32_e32 v36, v36
	v_exp_f32_e32 v37, v37
	v_add_f32_e32 v36, 1.0, v36
	v_add_f32_e32 v37, 1.0, v37
	v_rcp_f32_e32 v36, v36
	v_rcp_f32_e32 v37, v37
	s_nop 0
	v_pk_mul_f32 v[126:127], v[36:37], v[126:127]
	v_mul_f32_e32 v36, 0xbfb8aa3b, v45
	v_mul_f32_e32 v37, 0xbfb8aa3b, v39
	v_exp_f32_e32 v36, v36
	v_exp_f32_e32 v37, v37
	v_add_f32_e32 v36, 1.0, v36
	v_add_f32_e32 v37, 1.0, v37
	v_rcp_f32_e32 v36, v36
	v_rcp_f32_e32 v37, v37
	s_nop 0
	v_pk_mul_f32 v[128:129], v[36:37], v[128:129]
.LBB0_366:
	s_add_i32 s54, s60, 2
	s_and_b64 vcc, exec, s[40:41]
	s_ashr_i32 s55, s54, 31
	s_cbranch_vccnz .LBB0_397
	s_lshl_b64 s[8:9], s[54:55], 12
	v_lshl_add_u64 v[48:49], v[84:85], 0, s[8:9]
	global_load_dwordx4 v[36:39], v[48:49], off
	global_load_dwordx4 v[40:43], v[48:49], off offset:16
	global_load_dwordx4 v[44:47], v[48:49], off offset:2048
	s_nop 0
	global_load_dwordx4 v[48:51], v[48:49], off offset:2064
	s_lshl_b64 s[56:57], s[54:55], 11
	s_waitcnt vmcnt(0)
	s_cbranch_execnz .LBB0_369
.LBB0_368:
	s_lshl_b64 s[56:57], s[54:55], 11
	s_waitcnt vmcnt(2)
	v_mov_b32_e32 v40, v236
	v_mov_b32_e32 v41, v237
	v_mov_b32_e32 v42, v238
	v_mov_b32_e32 v43, v239
	v_mov_b32_e32 v48, v240
	v_mov_b32_e32 v49, v241
	v_mov_b32_e32 v50, v242
	v_mov_b32_e32 v51, v243
	v_lshlrev_b32_e32 v36, 16, v40
	v_and_b32_e32 v37, 0xffff0000, v40
	v_lshlrev_b32_e32 v38, 16, v41
	v_and_b32_e32 v39, 0xffff0000, v41
	v_lshlrev_b32_e32 v40, 16, v42
	v_and_b32_e32 v41, 0xffff0000, v42
	v_lshlrev_b32_e32 v42, 16, v43
	v_and_b32_e32 v43, 0xffff0000, v43
	s_waitcnt vmcnt(2)
	v_lshlrev_b32_e32 v44, 16, v48
	v_and_b32_e32 v45, 0xffff0000, v48
	v_lshlrev_b32_e32 v46, 16, v49
	v_and_b32_e32 v47, 0xffff0000, v49
	v_lshlrev_b32_e32 v48, 16, v50
	v_and_b32_e32 v49, 0xffff0000, v50
	v_lshlrev_b32_e32 v50, 16, v51
	v_and_b32_e32 v51, 0xffff0000, v51
.LBB0_369:
	s_and_b64 vcc, exec, s[42:43]
	s_waitcnt vmcnt(2)
	v_mov_b32_e32 v52, v212
	v_mov_b32_e32 v53, v213
	v_mov_b32_e32 v54, v214
	v_mov_b32_e32 v55, v215
	v_mov_b32_e32 v56, v216
	v_mov_b32_e32 v57, v217
	v_mov_b32_e32 v58, v218
	v_mov_b32_e32 v59, v219
	v_lshlrev_b32_e32 v154, 16, v52
	v_and_b32_e32 v155, 0xffff0000, v52
	v_lshlrev_b32_e32 v156, 16, v53
	v_and_b32_e32 v157, 0xffff0000, v53
	v_lshlrev_b32_e32 v142, 16, v54
	v_and_b32_e32 v143, 0xffff0000, v54
	v_lshlrev_b32_e32 v144, 16, v55
	v_and_b32_e32 v145, 0xffff0000, v55
	s_waitcnt vmcnt(2)
	v_lshlrev_b32_e32 v146, 16, v56
	v_and_b32_e32 v147, 0xffff0000, v56
	v_lshlrev_b32_e32 v148, 16, v57
	v_and_b32_e32 v149, 0xffff0000, v57
	v_lshlrev_b32_e32 v150, 16, v58
	v_and_b32_e32 v151, 0xffff0000, v58
	v_lshlrev_b32_e32 v152, 16, v59
	v_and_b32_e32 v153, 0xffff0000, v59
	s_cbranch_vccnz .LBB0_371
	v_lshl_add_u64 v[56:57], v[88:89], 0, s[56:57]
	global_load_dwordx4 v[52:55], v[56:57], off
	s_waitcnt vmcnt(0)
	v_lshlrev_b32_e32 v58, 16, v52
	v_and_b32_e32 v59, 0xffff0000, v52
	v_lshlrev_b32_e32 v60, 16, v53
	v_and_b32_e32 v61, 0xffff0000, v53
	v_mul_f32_e32 v52, 0xbfb8aa3b, v58
	v_mul_f32_e32 v53, 0xbfb8aa3b, v59
	v_exp_f32_e32 v52, v52
	v_exp_f32_e32 v53, v53
	v_lshlrev_b32_e32 v62, 16, v54
	v_and_b32_e32 v54, 0xffff0000, v54
	v_add_f32_e32 v52, 1.0, v52
	v_add_f32_e32 v53, 1.0, v53
	v_rcp_f32_e32 v52, v52
	v_rcp_f32_e32 v53, v53
	v_lshlrev_b32_e32 v63, 16, v55
	v_and_b32_e32 v55, 0xffff0000, v55
	v_pk_mul_f32 v[154:155], v[52:53], v[154:155]
	v_mul_f32_e32 v52, 0xbfb8aa3b, v60
	v_mul_f32_e32 v53, 0xbfb8aa3b, v61
	v_exp_f32_e32 v52, v52
	v_exp_f32_e32 v53, v53
	v_add_f32_e32 v52, 1.0, v52
	v_add_f32_e32 v53, 1.0, v53
	v_rcp_f32_e32 v52, v52
	v_rcp_f32_e32 v53, v53
	s_nop 0
	v_pk_mul_f32 v[156:157], v[52:53], v[156:157]
	v_mul_f32_e32 v52, 0xbfb8aa3b, v62
	v_mul_f32_e32 v53, 0xbfb8aa3b, v54
	v_exp_f32_e32 v52, v52
	v_exp_f32_e32 v53, v53
	v_add_f32_e32 v52, 1.0, v52
	v_add_f32_e32 v53, 1.0, v53
	v_rcp_f32_e32 v52, v52
	v_rcp_f32_e32 v53, v53
	s_nop 0
	v_pk_mul_f32 v[142:143], v[52:53], v[142:143]
	v_mul_f32_e32 v52, 0xbfb8aa3b, v63
	v_mul_f32_e32 v53, 0xbfb8aa3b, v55
	v_exp_f32_e32 v52, v52
	v_exp_f32_e32 v53, v53
	v_add_f32_e32 v52, 1.0, v52
	v_add_f32_e32 v53, 1.0, v53
	v_rcp_f32_e32 v52, v52
	v_rcp_f32_e32 v53, v53
	s_nop 0
	v_pk_mul_f32 v[144:145], v[52:53], v[144:145]
	global_load_dwordx4 v[52:55], v[56:57], off offset:1024
	s_waitcnt vmcnt(0)
	v_lshlrev_b32_e32 v56, 16, v52
	v_and_b32_e32 v57, 0xffff0000, v52
	v_lshlrev_b32_e32 v58, 16, v53
	v_and_b32_e32 v59, 0xffff0000, v53
	v_mul_f32_e32 v52, 0xbfb8aa3b, v56
	v_mul_f32_e32 v53, 0xbfb8aa3b, v57
	v_exp_f32_e32 v52, v52
	v_exp_f32_e32 v53, v53
	v_lshlrev_b32_e32 v60, 16, v54
	v_and_b32_e32 v54, 0xffff0000, v54
	v_add_f32_e32 v52, 1.0, v52
	v_add_f32_e32 v53, 1.0, v53
	v_rcp_f32_e32 v52, v52
	v_rcp_f32_e32 v53, v53
	v_lshlrev_b32_e32 v61, 16, v55
	v_and_b32_e32 v55, 0xffff0000, v55
	v_pk_mul_f32 v[146:147], v[52:53], v[146:147]
	v_mul_f32_e32 v52, 0xbfb8aa3b, v58
	v_mul_f32_e32 v53, 0xbfb8aa3b, v59
	v_exp_f32_e32 v52, v52
	v_exp_f32_e32 v53, v53
	v_add_f32_e32 v52, 1.0, v52
	v_add_f32_e32 v53, 1.0, v53
	v_rcp_f32_e32 v52, v52
	v_rcp_f32_e32 v53, v53
	s_nop 0
	v_pk_mul_f32 v[148:149], v[52:53], v[148:149]
	v_mul_f32_e32 v52, 0xbfb8aa3b, v60
	v_mul_f32_e32 v53, 0xbfb8aa3b, v54
	v_exp_f32_e32 v52, v52
	v_exp_f32_e32 v53, v53
	v_add_f32_e32 v52, 1.0, v52
	v_add_f32_e32 v53, 1.0, v53
	v_rcp_f32_e32 v52, v52
	v_rcp_f32_e32 v53, v53
	s_nop 0
	v_pk_mul_f32 v[150:151], v[52:53], v[150:151]
	v_mul_f32_e32 v52, 0xbfb8aa3b, v61
	v_mul_f32_e32 v53, 0xbfb8aa3b, v55
	v_exp_f32_e32 v52, v52
	v_exp_f32_e32 v53, v53
	v_add_f32_e32 v52, 1.0, v52
	v_add_f32_e32 v53, 1.0, v53
	v_rcp_f32_e32 v52, v52
	v_rcp_f32_e32 v53, v53
	s_nop 0
	v_pk_mul_f32 v[152:153], v[52:53], v[152:153]
.LBB0_371:
	s_add_i32 s36, s60, 3
	s_and_b64 vcc, exec, s[40:41]
	s_ashr_i32 s37, s36, 31
	s_cbranch_vccnz .LBB0_398
	s_lshl_b64 s[8:9], s[36:37], 12
	v_lshl_add_u64 v[64:65], v[84:85], 0, s[8:9]
	global_load_dwordx4 v[52:55], v[64:65], off
	global_load_dwordx4 v[56:59], v[64:65], off offset:16
	global_load_dwordx4 v[60:63], v[64:65], off offset:2048
	s_nop 0
	global_load_dwordx4 v[64:67], v[64:65], off offset:2064
	s_lshl_b64 s[58:59], s[36:37], 11
	s_waitcnt vmcnt(0)
	s_cbranch_execnz .LBB0_374
.LBB0_373:
	s_lshl_b64 s[58:59], s[36:37], 11
	s_waitcnt vmcnt(0)
	v_mov_b32_e32 v56, v228
	v_mov_b32_e32 v57, v229
	v_mov_b32_e32 v58, v230
	v_mov_b32_e32 v59, v231
	v_mov_b32_e32 v64, v232
	v_mov_b32_e32 v65, v233
	v_mov_b32_e32 v66, v234
	v_mov_b32_e32 v67, v235
	v_lshlrev_b32_e32 v52, 16, v56
	v_and_b32_e32 v53, 0xffff0000, v56
	v_lshlrev_b32_e32 v54, 16, v57
	v_and_b32_e32 v55, 0xffff0000, v57
	v_lshlrev_b32_e32 v56, 16, v58
	v_and_b32_e32 v57, 0xffff0000, v58
	v_lshlrev_b32_e32 v58, 16, v59
	v_and_b32_e32 v59, 0xffff0000, v59
	s_waitcnt vmcnt(0)
	v_lshlrev_b32_e32 v60, 16, v64
	v_and_b32_e32 v61, 0xffff0000, v64
	v_lshlrev_b32_e32 v62, 16, v65
	v_and_b32_e32 v63, 0xffff0000, v65
	v_lshlrev_b32_e32 v64, 16, v66
	v_and_b32_e32 v65, 0xffff0000, v66
	v_lshlrev_b32_e32 v66, 16, v67
	v_and_b32_e32 v67, 0xffff0000, v67
